# per-panel seams 2/3 + L2-shared granule exchange behind a run-time XCC co-location check (waits for the 8 published ids); placement-independent fallbacks validated separately
# baseline (speedup 1.0000x reference)
; __device__ __forceinline__ int lane_id() { int l; asm volatile("v_mbcnt_lo_u32_b32 %0, -1, 0\n\tv_mbcnt_hi_u32_b32 %0, -1, %0" : "=v"(l)); return l; }
; __device__ __forceinline__ void xcd_barrier(const XcdBarrier& b) {
;     asm volatile("s_waitcnt vmcnt(0)" ::: "memory");
;     __syncthreads();
;     if (b.w0 != 0 && lane_id() == 0) {
.LBB0_99:
	v_mbcnt_lo_u32_b32 v0, -1, 0
	v_mbcnt_hi_u32_b32 v0, -1, v0
	v_readlane_b32 s99, v254, 25
	s_and_b32 s99, s99, 0xffffffc7
	v_lshlrev_b32_e32 v0, 3, v0
	v_and_b32_e32 v0, 56, v0
	v_or_b32_e32 v0, s99, v0
	v_lshlrev_b32_e32 v0, 2, v0
	s_add_u32 s100, s34, 0x1c800
	s_addc_u32 s101, s35, 0
	global_load_dword v1, v0, s[100:101] sc1
	s_waitcnt vmcnt(0)
	s_movk_i32 s99, 0x2000
.Lcoloc_chk:
	v_cmp_eq_u32_e32 vcc, 0, v1
	s_cmp_eq_u64 vcc, 0
	s_cbranch_scc1 .Lcoloc_ok
	s_sub_u32 s99, s99, 1
	s_cmp_eq_u32 s99, 0
	s_cbranch_scc1 .Lcoloc_ok
	s_sleep 8
	global_load_dword v1, v0, s[100:101] sc1
	s_waitcnt vmcnt(0)
	s_branch .Lcoloc_chk
.Lcoloc_ok:
	v_readlane_b32 s99, v254, 5
	s_add_i32 s99, s99, 1
	v_cmp_ne_u32_e32 vcc, s99, v1
	s_cmp_lg_u64 vcc, 0
	s_cselect_b32 s98, 1, 0
	v_readlane_b32 s0, v254, 4
	s_cmp_gt_u32 s0, 63
	v_readlane_b32 s83, v254, 25
	v_readlane_b32 s84, v254, 8
	v_readlane_b32 s86, v254, 7
	s_barrier
	s_cbranch_scc1 .LBB0_153
	v_mbcnt_lo_u32_b32 v0, -1, 0
	v_mbcnt_hi_u32_b32 v0, -1, v0
	s_nop 0
	v_cmp_eq_u32_e32 vcc, 0, v0
	s_and_saveexec_b64 s[0:1], vcc
	s_cbranch_execz .LBB0_152
	s_add_i32 s2, 0, 0x20168
	v_mov_b32_e32 v0, s2
	s_waitcnt vmcnt(0) expcnt(0) lgkmcnt(0)
	ds_read_b32 v2, v0
	s_add_i32 s2, 0, 0x2016c
	v_mov_b32_e32 v0, s2
	ds_read_b32 v0, v0
	s_waitcnt lgkmcnt(1)
	v_cmp_ne_u32_e32 vcc, 0, v2
	s_cbranch_vccnz .LBB0_116
	s_add_u32 s2, s34, 0xae00
	s_addc_u32 s3, s35, 0
	s_add_u32 s4, s34, 0xb000
	s_addc_u32 s5, s35, 0
	s_add_u32 s6, s34, 0xb100
	s_addc_u32 s7, s35, 0
	s_add_u32 s8, s34, 0xb200
	s_addc_u32 s9, s35, 0
	s_add_u32 s10, s34, 0xb300
	s_addc_u32 s11, s35, 0
	s_add_u32 s12, s34, 0xb400
	s_addc_u32 s13, s35, 0
	s_add_u32 s14, s34, 0xb500
	s_addc_u32 s15, s35, 0
	s_add_u32 s16, s34, 0xb600
	s_addc_u32 s17, s35, 0
	s_add_u32 s20, s34, 0xb700
	s_addc_u32 s21, s35, 0
	s_add_u32 s24, s34, 0xb800
	s_addc_u32 s25, s35, 0
	s_add_u32 s36, s34, 0xb900
	s_addc_u32 s37, s35, 0
	s_add_u32 s40, s34, 0xba00
	s_addc_u32 s41, s35, 0
	s_add_u32 s42, s34, 0xbb00
	s_addc_u32 s43, s35, 0
	s_add_u32 s44, s34, 0xbc00
	s_addc_u32 s45, s35, 0
	s_add_u32 s46, s34, 0xbd00
	s_addc_u32 s47, s35, 0
	s_add_u32 s48, s34, 0xbe00
	s_addc_u32 s49, s35, 0
	s_add_u32 s50, s34, 0xbf00
	s_addc_u32 s51, s35, 0
	s_mov_b32 s66, 1
	v_mov_b32_e32 v16, 0
	s_movk_i32 s67, 0x100
	s_branch .LBB0_104
